# speedup vs baseline: 1.0009x; 1.0009x over previous
; template <bool SB>
; DEV void attn_pass(const bf16_t* __restrict__ proj, int qcol, int kcol, int vcol, int q0, f32x16 (&o)[4], float& l_out, unsigned char* lds) {
;     ...
;   for (int it = 0; it <= jhi; ++it) {
;     const int j = jhi - it, buf = it & 1;
;     if (it < jhi) SLOAD(j - 1);
;     bool wdone = false;
;     if (j <= jw) {
.LBB0_356:
	v_readfirstlane_b32 s90, v210
	s_nop 3
	s_cmp_lt_u32 s90, 0x100
	s_cbranch_scc1 .Lsb_nostag
	s_sleep 9
